# S5 readout issues its four LDS fragment reads together (counted lgkmcnt) instead of read-wait-MFMA per fragment
# speedup vs baseline: 1.0430x; 1.0020x over previous
; __device__ __forceinline__ void s5_wave(const Params& p, int l, int b, int g, int dir, char* Lw, bool ctx_out) {
;     ...
;   auto readout = [&](int cc) {
;     if (!((cc >= NCC) || ctx_out)) return;
;     const u16* Sb = Sbf + (cc & 1) * 2176;
;     f32x4 y = f32x4{0.f, 0.f, 0.f, 0.f};
; #pragma unroll
;     for (int ks = 0; ks < 4; ++ks) {
;       const bf16x8 sa = *reinterpret_cast<const bf16x8*>(Sb + fr * 136 + ks * 32 + fq * 8);
;       y = __builtin_amdgcn_mfma_f32_16x16x32_bf16(Cf[ks], sa, y, 0, 0, 0);
;     }
;     uint2 w;
;     w.x = pack2(y[0], y[1]); w.y = pack2(y[2], y[3]);
;     *reinterpret_cast<uint2*>(O + row_of(cc, fr) * 256 + g * 16 + fq * 4) = w;
.LBB0_1184:
	s_or_b64 exec, exec, s[0:1]
	s_cmp_eq_u32 s2, 0
	s_cbranch_scc1 .LBB0_1177
	s_add_i32 s6, s2, -1
	s_cmp_gt_u32 s6, 15
	s_cselect_b64 s[0:1], -1, 0
	s_or_b64 s[12:13], s[22:23], s[0:1]
	s_andn2_b64 vcc, exec, s[12:13]
	s_cbranch_vccnz .LBB0_1177
	s_bitcmp1_b32 s6, 0
	s_cselect_b32 s7, 0x1100, 0
	v_add_u32_e32 v101, s7, v109
	ds_read_b128 v[88:91], v101 offset:8960
	ds_read_b128 v[112:115], v101 offset:9024
	ds_read_b128 v[116:119], v101 offset:9088
	ds_read_b128 v[120:123], v101 offset:9152
	s_sub_i32 s7, s2, 17
	s_and_b64 s[12:13], s[0:1], exec
	s_cselect_b32 s12, s7, s6
	s_waitcnt lgkmcnt(3)
	v_mfma_f32_16x16x32_bf16 v[88:91], v[40:43], v[88:91], 0
	s_waitcnt lgkmcnt(2)
	v_mfma_f32_16x16x32_bf16 v[88:91], v[52:55], v[112:115], v[88:91]
	s_waitcnt lgkmcnt(1)
	v_mfma_f32_16x16x32_bf16 v[88:91], v[44:47], v[116:119], v[88:91]
	v_lshl_or_b32 v101, s12, 4, v106
	s_waitcnt lgkmcnt(0)
	v_mfma_f32_16x16x32_bf16 v[88:91], v[48:51], v[120:123], v[88:91]
	s_and_saveexec_b64 s[6:7], s[10:11]
	s_xor_b64 s[6:7], exec, s[6:7]
	s_cbranch_execz .LBB0_1176
	s_and_b64 s[18:19], s[0:1], exec
	s_cselect_b32 s13, s20, 0xff
	v_lshl_or_b32 v101, s12, 4, v106
	v_sub_u32_e32 v101, s13, v101
	s_branch .LBB0_1176
